# HGRN c3: each direction pass touches (dummy loads) the tiles the next pass will stage (LB of this item / LF,QH,IH of the block's next item)
# speedup vs baseline: 1.0105x; 1.0026x over previous
; DEV void phase_hg_c3(const Params& p, char* smem) {
;     ...
;       __syncthreads();
;       const int k = tid & 127, half = tid >> 7;
;       {
;         const bf16_t* lsrc = (dir ? LBp : LFp);
; #pragma unroll
;         for (int i = 0; i < 4; i++) {
;           int id = tid + i * 256; int s = id >> 4, cc = id & 15;
;           const size_t go = (size_t)(r0 + s) * 1024 + h * 128 + cc * 8;
;           uint4 u = *(const uint4*)(IH + go);
;           *(uint4*)(Kin + s * 144 + cc * 8) = *(const uint4*)(lsrc + go);
;           *(uint4*)(Qin + s * 144 + cc * 8) = *(const uint4*)(QH + go);
;           bf16_t* vt = Vt + (cc * 8) * 80 + s;
;           vt[0] = (bf16_t)(u.x & 0xffff); vt[80] = (bf16_t)(u.x >> 16); vt[160] = (bf16_t)(u.y & 0xffff); vt[240] = (bf16_t)(u.y >> 16);
;           vt[320] = (bf16_t)(u.z & 0xffff); vt[400] = (bf16_t)(u.z >> 16); vt[480] = (bf16_t)(u.w & 0xffff); vt[560] = (bf16_t)(u.w >> 16);
;         }
;       }
;       u32x4 spr[8];
;       {
;         const bf16_t* sp = DS + ((size_t)(bh * 2 + dir) * 132 + hg_step(cidx, dir)) * 16384;
; #pragma unroll
;         for (int i = 0; i < 8; i++) { int id = tid + i * 256; int row = id >> 4, cc = id & 15; spr[i] = *(const u32x4*)(sp + row * 128 + cc * 8); }
.LBB0_279:
	s_xor_b64 s[78:79], s[6:7], -1
	s_and_b64 s[14:15], s[6:7], exec
	s_mov_b32 s14, 0xe400000
	s_cselect_b32 s14, s14, 0x10500000
	s_add_u32 s14, s28, s14
	s_addc_u32 s15, s29, 0
	s_waitcnt vmcnt(19)
	v_lshl_add_u64 v[38:39], v[84:85], 1, s[14:15]
	v_lshl_add_u64 v[42:43], v[90:91], 1, s[14:15]
	v_lshl_add_u64 v[46:47], v[96:97], 1, s[14:15]
	v_lshl_add_u64 v[50:51], v[102:103], 1, s[14:15]
	v_lshl_add_u64 v[176:177], v[192:193], 0, v[244:245]
	v_lshl_add_u64 v[184:185], v[192:193], 1, v[244:245]
	v_lshl_add_u64 v[236:237], v[192:193], 0, v[184:185]
	s_waitcnt lgkmcnt(0)
	s_barrier
	global_load_dwordx4 v[38:41], v[38:39], off
	global_load_dwordx4 v[34:37], v[244:245], off
	global_load_dwordx4 v[172:175], v[88:89], off
	global_load_dwordx4 v[42:45], v[42:43], off
	global_load_dwordx4 v[176:179], v[176:177], off
	global_load_dwordx4 v[180:183], v[94:95], off
	global_load_dwordx4 v[46:49], v[46:47], off
	global_load_dwordx4 v[184:187], v[184:185], off
	global_load_dwordx4 v[188:191], v[100:101], off
	global_load_dwordx4 v[50:53], v[50:51], off
	global_load_dwordx4 v[236:239], v[236:237], off
	global_load_dwordx4 v[240:243], v[106:107], off
	s_waitcnt vmcnt(11)
	ds_write_b128 v133, v[38:41]
	s_waitcnt vmcnt(10)
	ds_write_b16 v194, v34 offset:36864
	ds_write_b16_d16_hi v194, v34 offset:37024
	ds_write_b16 v194, v35 offset:37184
	ds_write_b16_d16_hi v194, v35 offset:37344
	ds_write_b16 v194, v36 offset:37504
	ds_write_b16_d16_hi v194, v36 offset:37664
	ds_write_b16 v194, v37 offset:37824
	ds_write_b16_d16_hi v194, v37 offset:37984
	s_waitcnt vmcnt(9)
	ds_write_b128 v132, v[172:175]
	s_waitcnt vmcnt(8)
	ds_write_b128 v137, v[42:45]
	s_waitcnt vmcnt(7)
	ds_write_b16 v194, v176 offset:36896
	ds_write_b16_d16_hi v194, v176 offset:37056
	ds_write_b16 v194, v177 offset:37216
	ds_write_b16_d16_hi v194, v177 offset:37376
	ds_write_b16 v194, v178 offset:37536
	ds_write_b16_d16_hi v194, v178 offset:37696
	ds_write_b16 v194, v179 offset:37856
	ds_write_b16_d16_hi v194, v179 offset:38016
	s_waitcnt vmcnt(6)
	ds_write_b128 v136, v[180:183]
	s_waitcnt vmcnt(5)
	ds_write_b128 v141, v[46:49]
	s_waitcnt vmcnt(4)
	ds_write_b16 v194, v184 offset:36928
	ds_write_b16_d16_hi v194, v184 offset:37088
	ds_write_b16 v194, v185 offset:37248
	ds_write_b16_d16_hi v194, v185 offset:37408
	ds_write_b16 v194, v186 offset:37568
	ds_write_b16_d16_hi v194, v186 offset:37728
	ds_write_b16 v194, v187 offset:37888
	ds_write_b16_d16_hi v194, v187 offset:38048
	s_waitcnt vmcnt(3)
	ds_write_b128 v140, v[188:191]
	s_waitcnt vmcnt(2)
	ds_write_b128 v145, v[50:53]
	s_waitcnt vmcnt(1)
	ds_write_b16 v194, v236 offset:36960
	ds_write_b16_d16_hi v194, v236 offset:37120
	ds_write_b16 v194, v237 offset:37280
	ds_write_b16_d16_hi v194, v237 offset:37440
	ds_write_b16 v194, v238 offset:37600
	ds_write_b16_d16_hi v194, v238 offset:37760
	ds_write_b16 v194, v239 offset:37920
	ds_write_b16_d16_hi v194, v239 offset:38080
	s_waitcnt vmcnt(0)
	ds_write_b128 v144, v[240:243]
	s_cmp_lg_u64 s[6:7], 0
	s_cbranch_scc0 .Lc3_pf_dir1
	s_add_u32 s98, s14, 0x2100000
	s_addc_u32 s99, s15, 0
	v_lshl_add_u64 v[188:189], v[84:85], 1, s[98:99]
	global_load_dwordx4 v[184:187], v[188:189], off
	v_lshl_add_u64 v[188:189], v[90:91], 1, s[98:99]
	global_load_dwordx4 v[184:187], v[188:189], off
	v_lshl_add_u64 v[188:189], v[96:97], 1, s[98:99]
	global_load_dwordx4 v[184:187], v[188:189], off
	v_lshl_add_u64 v[188:189], v[102:103], 1, s[98:99]
	global_load_dwordx4 v[184:187], v[188:189], off
	s_branch .Lc3_pf_done
.Lc3_pf_dir1:
	s_sub_u32 s98, s14, 0x1d00000
	s_subb_u32 s99, s15, 0
	v_lshl_add_u64 v[188:189], v[84:85], 1, s[98:99]
	global_load_dwordx4 v[184:187], v[188:189], off
	v_lshl_add_u64 v[188:189], v[90:91], 1, s[98:99]
	global_load_dwordx4 v[184:187], v[188:189], off
	v_lshl_add_u64 v[188:189], v[96:97], 1, s[98:99]
	global_load_dwordx4 v[184:187], v[188:189], off
	v_lshl_add_u64 v[188:189], v[102:103], 1, s[98:99]
	global_load_dwordx4 v[184:187], v[188:189], off
	s_mov_b32 s98, 0x400000
	s_mov_b32 s99, 0
	v_lshl_add_u64 v[188:189], v[88:89], 0, s[98:99]
	global_load_dwordx4 v[184:187], v[188:189], off
	v_lshl_add_u64 v[188:189], v[94:95], 0, s[98:99]
	global_load_dwordx4 v[184:187], v[188:189], off
	v_lshl_add_u64 v[188:189], v[100:101], 0, s[98:99]
	global_load_dwordx4 v[184:187], v[188:189], off
	v_lshl_add_u64 v[188:189], v[106:107], 0, s[98:99]
	global_load_dwordx4 v[184:187], v[188:189], off
	v_lshl_add_u64 v[188:189], v[244:245], 0, s[98:99]
	global_load_dwordx4 v[184:187], v[188:189], off
	s_add_u32 s98, s98, 0x8000
	v_lshl_add_u64 v[188:189], v[244:245], 0, s[98:99]
	global_load_dwordx4 v[184:187], v[188:189], off
	s_add_u32 s98, s98, 0x8000
	v_lshl_add_u64 v[188:189], v[244:245], 0, s[98:99]
	global_load_dwordx4 v[184:187], v[188:189], off
	s_add_u32 s98, s98, 0x8000
	v_lshl_add_u64 v[188:189], v[244:245], 0, s[98:99]
	global_load_dwordx4 v[184:187], v[188:189], off
.Lc3_pf_done:
	v_mov_b32_e32 v0, 0
	s_or_b32 s14, s20, s44
	s_and_b64 s[6:7], s[6:7], exec
	s_cselect_b32 s6, s51, s45
	s_mulk_i32 s14, 0x84
	s_ashr_i32 s7, s6, 31
	s_add_u32 s6, s14, s6
	s_addc_u32 s7, 0, s7
	s_lshl_b64 s[6:7], s[6:7], 15
	v_lshl_add_u64 v[62:63], v[66:67], 0, s[6:7]
	v_lshl_add_u64 v[42:43], v[72:73], 1, v[62:63]
	v_lshl_add_u64 v[46:47], v[74:75], 1, v[62:63]
	v_lshl_add_u64 v[50:51], v[76:77], 1, v[62:63]
	v_lshl_add_u64 v[54:55], v[78:79], 1, v[62:63]
	v_lshl_add_u64 v[58:59], v[80:81], 1, v[62:63]
	s_mov_b32 s6, 0
	v_lshl_add_u64 v[34:35], v[68:69], 1, v[62:63]
	v_lshl_add_u64 v[38:39], v[70:71], 1, v[62:63]
	v_lshl_add_u64 v[62:63], v[82:83], 1, v[62:63]
	global_load_dwordx4 v[34:37], v[34:35], off
	s_nop 0
	global_load_dwordx4 v[38:41], v[38:39], off
	s_nop 0
	global_load_dwordx4 v[42:45], v[42:43], off
	s_nop 0
	global_load_dwordx4 v[46:49], v[46:47], off
	s_nop 0
	global_load_dwordx4 v[50:53], v[50:51], off
	s_nop 0
	global_load_dwordx4 v[54:57], v[54:55], off
	s_nop 0
	global_load_dwordx4 v[58:61], v[58:59], off
	s_nop 0
	global_load_dwordx4 v[62:65], v[62:63], off
	s_waitcnt lgkmcnt(0)
	s_barrier
